# postproj: four tokens per wave preloaded per tile (24 loads in flight, one wait), cache-row conversion deferred into the same round trip
# baseline (speedup 1.0000x reference)
.LBB0_587:
	s_and_saveexec_b64 s[16:17], s[6:7]
	s_cbranch_execz .LBB0_589
	s_ashr_i32 s18, s0, 6
	s_and_b32 s18, s18, -4
	v_readlane_b32 s22, v251, 42
	s_add_i32 s18, s18, s22
	s_and_b32 s20, s0, 0xff
	s_ashr_i32 s19, s18, 31
	v_lshlrev_b32_e64 v2, v114, s20
	v_lshlrev_b64 v[16:17], v48, s[18:19]
	v_lshl_add_u64 v[16:17], v[50:51], 0, v[16:17]
	v_lshlrev_b32_e32 v2, 2, v2
	v_lshl_add_u64 v[16:17], v[16:17], 0, v[2:3]
	v_lshl_add_u64 v[16:17], v[52:53], 2, v[16:17]
	global_load_dword v239, v[16:17], off
	s_add_i32 s18, s0, 0x4000
	s_ashr_i32 s19, s18, 31
	v_lshlrev_b64 v[224:225], v54, s[18:19]
	v_lshl_add_u64 v[224:225], v[56:57], 0, v[224:225]
	v_readlane_b32 s23, v251, 43
.LBB0_589:
	s_or_b64 exec, exec, s[16:17]
	s_lshl_b32 s20, s0, 5
	s_bfe_u32 s16, s0, 0x60001
	v_or_b32_e32 v76, s20, v49
	v_cvt_f32_ubyte0_e32 v119, s16
	s_ashr_i32 s16, s0, 1
	v_readlane_b32 s18, v251, 42
	v_ashrrev_i32_e32 v77, 31, v76
	s_and_b32 s16, s16, -4
	v_readlane_b32 s19, v251, 43
	v_lshlrev_b64 v[16:17], 6, v[76:77]
	s_movk_i32 s21, 0x1200
	s_add_i32 s16, s16, s18
	v_lshl_add_u64 v[78:79], v[58:59], 0, v[16:17]
	v_lshlrev_b64 v[16:17], 8, v[76:77]
	v_mad_i64_i32 v[84:85], s[18:19], v76, s21, v[64:65]
	v_mad_i64_i32 v[86:87], s[18:19], v76, s21, v[66:67]
	v_mad_i64_i32 v[88:89], s[18:19], v76, s21, v[32:33]
	v_mad_i64_i32 v[90:91], s[18:19], v76, s21, v[68:69]
	v_lshl_add_u64 v[80:81], v[60:61], 0, v[16:17]
	v_lshlrev_b64 v[16:17], 9, v[76:77]
	v_or_b32_e32 v2, s20, v116
	s_mul_hi_i32 s18, s16, 0x60000
	s_mul_i32 s19, s16, 0x60000
	v_lshl_add_u64 v[82:83], v[62:63], 0, v[16:17]
	v_mov_b32_e32 v17, s18
	v_or_b32_e32 v16, s19, v36
	v_and_b32_e32 v18, 0xff, v2
	s_movk_i32 s18, 0x600
	s_ashr_i32 s17, s16, 31
	v_mad_u64_u32 v[92:93], s[18:19], v18, s18, v[16:17]
	s_lshl_b64 s[18:19], s[16:17], 17
	s_lshl_b64 s[22:23], s[16:17], 8
	v_and_b32_e32 v77, 63, v2
	v_lshl_add_u64 v[16:17], v[70:71], 0, s[18:19]
	v_lshlrev_b32_e32 v2, 9, v18
	s_lshl_b64 s[16:17], s[16:17], 15
	v_lshl_add_u64 v[94:95], v[16:17], 0, v[2:3]
	v_lshl_add_u64 v[16:17], v[72:73], 0, s[16:17]
	v_lshlrev_b32_e32 v18, 7, v18
	v_mov_b32_e32 v19, v3
	v_lshl_add_u64 v[96:97], v[16:17], 0, v[18:19]
	v_lshl_add_u64 v[16:17], v[74:75], 0, s[18:19]
	v_lshl_add_u64 v[98:99], v[16:17], 0, v[2:3]
	v_cmp_gt_i32_e64 s[18:19], s95, v76
	s_and_b64 s[24:25], s[2:3], s[18:19]
	s_mov_b32 s99, 0
	s_movk_i32 s98, 0x0
	v_lshl_add_u64 v[122:123], v[88:89], 0, s[98:99]
	v_lshl_add_u64 v[100:101], s[88:89], 0, v[122:123]
	v_mov_b32_e32 v134, 0
	v_mov_b32_e32 v135, 0
	v_mov_b32_e32 v136, 0
	v_mov_b32_e32 v137, 0
	s_and_saveexec_b64 s[26:27], s[24:25]
	v_add_co_u32_e32 v16, vcc, 0x8198000, v100
	s_nop 1
	v_addc_co_u32_e32 v17, vcc, 0, v101, vcc
	global_load_dwordx4 v[134:137], v[16:17], off offset:768
	s_or_b64 exec, exec, s[26:27]
	s_mov_b64 s[26:27], 0x8198600
	v_lshl_add_u64 v[16:17], v[100:101], 0, s[26:27]
	s_mov_b64 s[26:27], 0x8198d00
	v_lshl_add_u64 v[18:19], v[100:101], 0, s[26:27]
	v_cndmask_b32_e64 v17, v19, v17, s[2:3]
	v_cndmask_b32_e64 v16, v18, v16, s[2:3]
	global_load_dwordx4 v[138:141], v[16:17], off
	v_lshl_add_u64 v[16:17], v[86:87], 0, s[98:99]
	v_lshl_add_u64 v[18:19], v[84:85], 0, s[98:99]
	v_lshl_add_u64 v[16:17], s[88:89], 0, v[16:17]
	v_lshl_add_u64 v[18:19], s[88:89], 0, v[18:19]
	global_load_dwordx2 v[142:143], v[16:17], off
	global_load_dword v152, v[18:19], off
	v_add_co_u32_e32 v16, vcc, 0x8198000, v100
	v_lshl_add_u64 v[18:19], v[90:91], 0, s[98:99]
	v_lshl_add_u64 v[18:19], s[88:89], 0, v[18:19]
	v_addc_co_u32_e32 v17, vcc, 0, v101, vcc
	global_load_dwordx4 v[144:147], v[16:17], off offset:3072
	global_load_dwordx4 v[148:151], v[18:19], off
	s_movk_i32 s98, 0x1200
	v_lshl_add_u64 v[122:123], v[88:89], 0, s[98:99]
	v_lshl_add_u64 v[100:101], s[88:89], 0, v[122:123]
	v_mov_b32_e32 v154, 0
	v_mov_b32_e32 v155, 0
	v_mov_b32_e32 v156, 0
	v_mov_b32_e32 v157, 0
	s_and_saveexec_b64 s[26:27], s[24:25]
	v_add_co_u32_e32 v16, vcc, 0x8198000, v100
	s_nop 1
	v_addc_co_u32_e32 v17, vcc, 0, v101, vcc
	global_load_dwordx4 v[154:157], v[16:17], off offset:768
	s_or_b64 exec, exec, s[26:27]
	s_mov_b64 s[26:27], 0x8198600
	v_lshl_add_u64 v[16:17], v[100:101], 0, s[26:27]
	s_mov_b64 s[26:27], 0x8198d00
	v_lshl_add_u64 v[18:19], v[100:101], 0, s[26:27]
	v_cndmask_b32_e64 v17, v19, v17, s[2:3]
	v_cndmask_b32_e64 v16, v18, v16, s[2:3]
	global_load_dwordx4 v[158:161], v[16:17], off
	v_lshl_add_u64 v[16:17], v[86:87], 0, s[98:99]
	v_lshl_add_u64 v[18:19], v[84:85], 0, s[98:99]
	v_lshl_add_u64 v[16:17], s[88:89], 0, v[16:17]
	v_lshl_add_u64 v[18:19], s[88:89], 0, v[18:19]
	global_load_dwordx2 v[162:163], v[16:17], off
	global_load_dword v172, v[18:19], off
	v_add_co_u32_e32 v16, vcc, 0x8198000, v100
	v_lshl_add_u64 v[18:19], v[90:91], 0, s[98:99]
	v_lshl_add_u64 v[18:19], s[88:89], 0, v[18:19]
	v_addc_co_u32_e32 v17, vcc, 0, v101, vcc
	global_load_dwordx4 v[164:167], v[16:17], off offset:3072
	global_load_dwordx4 v[168:171], v[18:19], off
	s_movk_i32 s98, 0x2400
	v_lshl_add_u64 v[122:123], v[88:89], 0, s[98:99]
	v_lshl_add_u64 v[100:101], s[88:89], 0, v[122:123]
	v_mov_b32_e32 v174, 0
	v_mov_b32_e32 v175, 0
	v_mov_b32_e32 v176, 0
	v_mov_b32_e32 v177, 0
	s_and_saveexec_b64 s[26:27], s[24:25]
	v_add_co_u32_e32 v16, vcc, 0x8198000, v100
	s_nop 1
	v_addc_co_u32_e32 v17, vcc, 0, v101, vcc
	global_load_dwordx4 v[174:177], v[16:17], off offset:768
	s_or_b64 exec, exec, s[26:27]
	s_mov_b64 s[26:27], 0x8198600
	v_lshl_add_u64 v[16:17], v[100:101], 0, s[26:27]
	s_mov_b64 s[26:27], 0x8198d00
	v_lshl_add_u64 v[18:19], v[100:101], 0, s[26:27]
	v_cndmask_b32_e64 v17, v19, v17, s[2:3]
	v_cndmask_b32_e64 v16, v18, v16, s[2:3]
	global_load_dwordx4 v[194:197], v[16:17], off
	v_lshl_add_u64 v[16:17], v[86:87], 0, s[98:99]
	v_lshl_add_u64 v[18:19], v[84:85], 0, s[98:99]
	v_lshl_add_u64 v[16:17], s[88:89], 0, v[16:17]
	v_lshl_add_u64 v[18:19], s[88:89], 0, v[18:19]
	global_load_dwordx2 v[198:199], v[16:17], off
	global_load_dword v178, v[18:19], off
	v_add_co_u32_e32 v16, vcc, 0x8198000, v100
	v_lshl_add_u64 v[18:19], v[90:91], 0, s[98:99]
	v_lshl_add_u64 v[18:19], s[88:89], 0, v[18:19]
	v_addc_co_u32_e32 v17, vcc, 0, v101, vcc
	global_load_dwordx4 v[200:203], v[16:17], off offset:3072
	global_load_dwordx4 v[204:207], v[18:19], off
	s_movk_i32 s98, 0x3600
	v_lshl_add_u64 v[122:123], v[88:89], 0, s[98:99]
	v_lshl_add_u64 v[100:101], s[88:89], 0, v[122:123]
	v_mov_b32_e32 v208, 0
	v_mov_b32_e32 v209, 0
	v_mov_b32_e32 v210, 0
	v_mov_b32_e32 v211, 0
	s_and_saveexec_b64 s[26:27], s[24:25]
	v_add_co_u32_e32 v16, vcc, 0x8198000, v100
	s_nop 1
	v_addc_co_u32_e32 v17, vcc, 0, v101, vcc
	global_load_dwordx4 v[208:211], v[16:17], off offset:768
	s_or_b64 exec, exec, s[26:27]
	s_mov_b64 s[26:27], 0x8198600
	v_lshl_add_u64 v[16:17], v[100:101], 0, s[26:27]
	s_mov_b64 s[26:27], 0x8198d00
	v_lshl_add_u64 v[18:19], v[100:101], 0, s[26:27]
	v_cndmask_b32_e64 v17, v19, v17, s[2:3]
	v_cndmask_b32_e64 v16, v18, v16, s[2:3]
	global_load_dwordx4 v[212:215], v[16:17], off
	v_lshl_add_u64 v[16:17], v[86:87], 0, s[98:99]
	v_lshl_add_u64 v[18:19], v[84:85], 0, s[98:99]
	v_lshl_add_u64 v[16:17], s[88:89], 0, v[16:17]
	v_lshl_add_u64 v[18:19], s[88:89], 0, v[18:19]
	global_load_dwordx2 v[216:217], v[16:17], off
	global_load_dword v222, v[18:19], off
	v_add_co_u32_e32 v16, vcc, 0x8198000, v100
	v_lshl_add_u64 v[18:19], v[90:91], 0, s[98:99]
	v_lshl_add_u64 v[18:19], s[88:89], 0, v[18:19]
	v_addc_co_u32_e32 v17, vcc, 0, v101, vcc
	global_load_dwordx4 v[218:221], v[16:17], off offset:3072
	global_load_dwordx4 v[240:243], v[18:19], off
	s_mov_b32 s21, 0
	v_mov_b32_e32 v2, v115
	s_branch .LBB0_591

.LBB0_591:
	v_add_u32_e32 v16, s21, v76
	s_movk_i32 s16, 0x1fff
	v_cmp_gt_i32_e64 s[18:19], s95, v16
	v_cmp_lt_i32_e64 s[16:17], s16, v16
	s_and_b64 s[24:25], s[2:3], s[18:19]
	s_waitcnt lgkmcnt(0)
	v_lshl_add_u64 v[100:101], s[88:89], 0, v[88:89]
	s_cmp_lg_u32 s21, 0
	s_cbranch_scc1 .Lpp_b1t
	s_waitcnt vmcnt(0)
	s_and_saveexec_b64 s[26:27], s[6:7]
	v_cvt_pk_bf16_f32 v239, v239, s0
	global_store_short v[224:225], v239, off
	s_or_b64 exec, exec, s[26:27]
	v_mov_b32_e32 v28, v134
	v_mov_b32_e32 v29, v135
	v_mov_b32_e32 v30, v136
	v_mov_b32_e32 v31, v137
	v_mov_b32_e32 v24, v138
	v_mov_b32_e32 v25, v139
	v_mov_b32_e32 v26, v140
	v_mov_b32_e32 v27, v141
	v_mov_b32_e32 v102, v142
	v_mov_b32_e32 v103, v143
	v_mov_b32_e32 v120, v152
	v_mov_b32_e32 v20, v144
	v_mov_b32_e32 v21, v145
	v_mov_b32_e32 v22, v146
	v_mov_b32_e32 v23, v147
	v_mov_b32_e32 v16, v148
	v_mov_b32_e32 v17, v149
	v_mov_b32_e32 v18, v150
	v_mov_b32_e32 v19, v151
	s_branch .Lpp_cont
.Lpp_b1t:
	s_cmp_lg_u32 s21, 1
	s_cbranch_scc1 .Lpp_b2t
	v_mov_b32_e32 v28, v154
	v_mov_b32_e32 v29, v155
	v_mov_b32_e32 v30, v156
	v_mov_b32_e32 v31, v157
	v_mov_b32_e32 v24, v158
	v_mov_b32_e32 v25, v159
	v_mov_b32_e32 v26, v160
	v_mov_b32_e32 v27, v161
	v_mov_b32_e32 v102, v162
	v_mov_b32_e32 v103, v163
	v_mov_b32_e32 v120, v172
	v_mov_b32_e32 v20, v164
	v_mov_b32_e32 v21, v165
	v_mov_b32_e32 v22, v166
	v_mov_b32_e32 v23, v167
	v_mov_b32_e32 v16, v168
	v_mov_b32_e32 v17, v169
	v_mov_b32_e32 v18, v170
	v_mov_b32_e32 v19, v171
	s_branch .Lpp_cont
.Lpp_b2t:
	s_cmp_lg_u32 s21, 2
	s_cbranch_scc1 .Lpp_b3
	v_mov_b32_e32 v28, v174
	v_mov_b32_e32 v29, v175
	v_mov_b32_e32 v30, v176
	v_mov_b32_e32 v31, v177
	v_mov_b32_e32 v24, v194
	v_mov_b32_e32 v25, v195
	v_mov_b32_e32 v26, v196
	v_mov_b32_e32 v27, v197
	v_mov_b32_e32 v102, v198
	v_mov_b32_e32 v103, v199
	v_mov_b32_e32 v120, v178
	v_mov_b32_e32 v20, v200
	v_mov_b32_e32 v21, v201
	v_mov_b32_e32 v22, v202
	v_mov_b32_e32 v23, v203
	v_mov_b32_e32 v16, v204
	v_mov_b32_e32 v17, v205
	v_mov_b32_e32 v18, v206
	v_mov_b32_e32 v19, v207
	s_branch .Lpp_cont
.Lpp_b3:
	v_mov_b32_e32 v28, v208
	v_mov_b32_e32 v29, v209
	v_mov_b32_e32 v30, v210
	v_mov_b32_e32 v31, v211
	v_mov_b32_e32 v24, v212
	v_mov_b32_e32 v25, v213
	v_mov_b32_e32 v26, v214
	v_mov_b32_e32 v27, v215
	v_mov_b32_e32 v102, v216
	v_mov_b32_e32 v103, v217
	v_mov_b32_e32 v120, v222
	v_mov_b32_e32 v20, v218
	v_mov_b32_e32 v21, v219
	v_mov_b32_e32 v22, v220
	v_mov_b32_e32 v23, v221
	v_mov_b32_e32 v16, v240
	v_mov_b32_e32 v17, v241
	v_mov_b32_e32 v18, v242
	v_mov_b32_e32 v19, v243
.Lpp_cont:
	s_and_saveexec_b64 s[26:27], s[24:25]
	s_cbranch_execz .LBB0_595
	v_lshl_add_u64 v[126:127], s[86:87], 0, v[92:93]
	v_add_co_u32_e32 v126, vcc, 0x4000000, v126
	v_lshlrev_b32_e32 v122, 16, v28
	v_and_b32_e32 v123, 0xffff0000, v28
	v_lshlrev_b32_e32 v124, 16, v29
	v_and_b32_e32 v125, 0xffff0000, v29
	v_addc_co_u32_e32 v127, vcc, 0, v127, vcc
	v_lshlrev_b32_e32 v28, 16, v30
	v_and_b32_e32 v29, 0xffff0000, v30
	v_lshlrev_b32_e32 v30, 16, v31
	v_and_b32_e32 v31, 0xffff0000, v31
	global_store_dwordx4 v[126:127], v[122:125], off
	global_store_dwordx4 v[126:127], v[28:31], off offset:16
.LBB0_595:
	s_or_b64 exec, exec, s[26:27]
	ds_write_b128 v2, v[24:27]
	s_and_saveexec_b64 s[24:25], s[18:19]
	s_cbranch_execz .LBB0_601
	s_and_saveexec_b64 s[26:27], s[4:5]
	s_xor_b64 s[26:27], exec, s[26:27]
	s_cbranch_execz .LBB0_598
	v_or_b32_e32 v28, s21, v49
	v_mov_b32_e32 v29, s20
	s_movk_i32 s28, 0xff
	v_bitop3_b32 v28, v28, s28, v29 bitop3:0xc8
	v_or_b32_e32 v28, s22, v28
	v_mov_b32_e32 v29, s23
	v_lshlrev_b64 v[28:29], 9, v[28:29]
	v_lshl_add_u64 v[28:29], v[38:39], 0, v[28:29]
	s_mov_b64 s[28:29], 0xc3ffa00
	v_lshl_add_u64 v[28:29], v[28:29], 0, s[28:29]
